# v57 + up K-loop fragment registers renamed: first-operand tuples and all second-operand tuples at index 0 mod 4, accumulators 2 mod 4
# speedup vs baseline: 1.0005x; 1.0005x over previous
.LBB0_158:
	s_ashr_i32 s15, s14, 31
	s_lshl_b64 s[16:17], s[14:15], 20
	s_add_u32 s16, s3, s16
	s_addc_u32 s17, s28, s17
	s_and_b64 s[18:19], s[4:5], exec
	s_cselect_b32 s15, s17, s23
	s_cselect_b32 s46, s16, s22
	s_ashr_i32 s13, s12, 31
	s_lshl_b64 s[18:19], s[12:13], 20
	s_add_u32 s18, s29, s18
	s_addc_u32 s19, s30, s19
	s_and_b64 s[26:27], s[4:5], exec
	s_cselect_b32 s13, s19, s25
	s_cselect_b32 s47, s18, s24
	s_add_u32 s22, s22, 0x80080
	s_addc_u32 s23, s23, 0
	s_add_u32 s48, s24, 0x100
	s_addc_u32 s49, s25, 0
	s_mov_b32 s50, -2
	s_add_u32 s0, s22, 0xfff80080
	s_addc_u32 s1, s23, -1
	s_add_i32 s51, 0, 0x10000
	s_cmp_eq_u32 s50, 28
	s_cselect_b32 s27, s15, s1
	s_cselect_b32 s26, s46, s0
	v_add_u32_e32 v140, s51, v143
	s_cselect_b32 s25, s13, s49
	s_cselect_b32 s24, s47, s48
	s_add_i32 s0, 0, 0x14000
	ds_read_b128 v[148:151], v140
	ds_read_b128 v[152:155], v140 offset:1024
	ds_read_b128 v[156:159], v140 offset:2048
	ds_read_b128 v[160:163], v140 offset:3072
	v_add_u32_e32 v140, s0, v143
	ds_read_b128 v[164:167], v140
	ds_read_b128 v[168:171], v140 offset:1024
	ds_read_b128 v[172:175], v140 offset:2048
	ds_read_b128 v[176:179], v140 offset:3072
	s_add_i32 m0, s35, 0xc000
	ds_read_b128 v[216:219], v144
	ds_read_b128 v[220:223], v144 offset:1024
	ds_read_b128 v[192:195], v144 offset:2048
	ds_read_b128 v[196:199], v144 offset:3072
	ds_read_b128 v[200:203], v144 offset:4096
	ds_read_b128 v[204:207], v144 offset:5120
	ds_read_b128 v[208:211], v144 offset:6144
	ds_read_b128 v[212:215], v144 offset:7168
	global_load_lds_dwordx4 v136, s[22:23]
	s_add_i32 m0, s35, 0xe000
	s_nop 0
	global_load_lds_dwordx4 v138, s[22:23]
	s_waitcnt vmcnt(8)
	s_waitcnt lgkmcnt(0)
	s_setprio 1
	s_barrier

	v_mfma_f32_16x16x32_bf16 v[126:129], v[148:151], v[216:219], 0
	v_mfma_f32_16x16x32_bf16 v[126:129], v[152:155], v[220:223], v[126:129]
	v_mfma_f32_16x16x32_bf16 v[118:121], v[160:163], v[220:223], 0
	v_mfma_f32_16x16x32_bf16 v[118:121], v[156:159], v[216:219], v[118:121]
	v_mfma_f32_16x16x32_bf16 v[102:105], v[156:159], v[192:195], 0
	v_mfma_f32_16x16x32_bf16 v[102:105], v[160:163], v[196:199], v[102:105]
	v_mfma_f32_16x16x32_bf16 v[110:113], v[152:155], v[196:199], 0
	v_mfma_f32_16x16x32_bf16 v[110:113], v[148:151], v[192:195], v[110:113]
	v_mfma_f32_16x16x32_bf16 v[94:97], v[148:151], v[200:203], 0
	v_mfma_f32_16x16x32_bf16 v[94:97], v[152:155], v[204:207], v[94:97]
	v_mfma_f32_16x16x32_bf16 v[86:89], v[160:163], v[204:207], 0
	v_mfma_f32_16x16x32_bf16 v[86:89], v[156:159], v[200:203], v[86:89]
	v_mfma_f32_16x16x32_bf16 v[70:73], v[156:159], v[208:211], 0
	v_mfma_f32_16x16x32_bf16 v[70:73], v[160:163], v[212:215], v[70:73]
	v_mfma_f32_16x16x32_bf16 v[78:81], v[152:155], v[212:215], 0
	v_mfma_f32_16x16x32_bf16 v[78:81], v[148:151], v[208:211], v[78:81]


	v_mfma_f32_16x16x32_bf16 v[122:125], v[164:167], v[216:219], 0
	v_mfma_f32_16x16x32_bf16 v[122:125], v[168:171], v[220:223], v[122:125]
	v_mfma_f32_16x16x32_bf16 v[114:117], v[176:179], v[220:223], 0
	v_mfma_f32_16x16x32_bf16 v[114:117], v[172:175], v[216:219], v[114:117]
	v_mfma_f32_16x16x32_bf16 v[98:101], v[172:175], v[192:195], 0
	v_mfma_f32_16x16x32_bf16 v[98:101], v[176:179], v[196:199], v[98:101]
	v_mfma_f32_16x16x32_bf16 v[106:109], v[168:171], v[196:199], 0
	v_mfma_f32_16x16x32_bf16 v[106:109], v[164:167], v[192:195], v[106:109]
	v_mfma_f32_16x16x32_bf16 v[90:93], v[164:167], v[200:203], 0
	v_mfma_f32_16x16x32_bf16 v[90:93], v[168:171], v[204:207], v[90:93]
	v_mfma_f32_16x16x32_bf16 v[82:85], v[176:179], v[204:207], 0
	v_mfma_f32_16x16x32_bf16 v[82:85], v[172:175], v[200:203], v[82:85]
	v_mfma_f32_16x16x32_bf16 v[66:69], v[172:175], v[208:211], 0
	v_mfma_f32_16x16x32_bf16 v[66:69], v[176:179], v[212:215], v[66:69]
	v_mfma_f32_16x16x32_bf16 v[74:77], v[168:171], v[212:215], 0
	v_mfma_f32_16x16x32_bf16 v[74:77], v[164:167], v[208:211], v[74:77]
	s_barrier
	s_setprio 0
	s_add_i32 s1, s51, s31
	s_mov_b32 m0, s1
	ds_read_b128 v[216:219], v144 offset:16384
	ds_read_b128 v[220:223], v144 offset:17408
	ds_read_b128 v[192:195], v144 offset:18432
	ds_read_b128 v[196:199], v144 offset:19456
	ds_read_b128 v[200:203], v144 offset:20480
	ds_read_b128 v[204:207], v144 offset:21504
	ds_read_b128 v[208:211], v144 offset:22528
	ds_read_b128 v[212:215], v144 offset:23552
	global_load_lds_dwordx4 v186, s[24:25]
	s_add_i32 m0, s1, 0x2000
	s_add_u32 s52, s24, 0x80000
	s_addc_u32 s53, s25, 0
	s_add_i32 s0, s0, s31
	global_load_lds_dwordx4 v130, s[24:25]
	s_mov_b32 m0, s0
	s_nop 0
	global_load_lds_dwordx4 v186, s[52:53]
	s_add_i32 m0, s0, 0x2000
	s_nop 0
	global_load_lds_dwordx4 v130, s[52:53]
	s_mov_b32 m0, s35
	s_nop 0
	global_load_lds_dwordx4 v134, s[26:27]
	s_mov_b32 m0, s36
	s_nop 0
	global_load_lds_dwordx4 v132, s[26:27]
	s_waitcnt vmcnt(8)
	s_waitcnt lgkmcnt(0)
	s_setprio 1
	s_barrier

	v_mfma_f32_16x16x32_bf16 v[62:65], v[148:151], v[216:219], 0
	v_mfma_f32_16x16x32_bf16 v[62:65], v[152:155], v[220:223], v[62:65]
	v_mfma_f32_16x16x32_bf16 v[54:57], v[160:163], v[220:223], 0
	v_mfma_f32_16x16x32_bf16 v[54:57], v[156:159], v[216:219], v[54:57]
	v_mfma_f32_16x16x32_bf16 v[38:41], v[156:159], v[192:195], 0
	v_mfma_f32_16x16x32_bf16 v[38:41], v[160:163], v[196:199], v[38:41]
	v_mfma_f32_16x16x32_bf16 v[46:49], v[152:155], v[196:199], 0
	v_mfma_f32_16x16x32_bf16 v[46:49], v[148:151], v[192:195], v[46:49]
	v_mfma_f32_16x16x32_bf16 v[30:33], v[148:151], v[200:203], 0
	v_mfma_f32_16x16x32_bf16 v[30:33], v[152:155], v[204:207], v[30:33]
	v_mfma_f32_16x16x32_bf16 v[22:25], v[160:163], v[204:207], 0
	v_mfma_f32_16x16x32_bf16 v[22:25], v[156:159], v[200:203], v[22:25]
	v_mfma_f32_16x16x32_bf16 v[6:9], v[156:159], v[208:211], 0
	v_mfma_f32_16x16x32_bf16 v[6:9], v[160:163], v[212:215], v[6:9]
	v_mfma_f32_16x16x32_bf16 v[14:17], v[152:155], v[212:215], 0
	v_mfma_f32_16x16x32_bf16 v[14:17], v[148:151], v[208:211], v[14:17]


	v_mfma_f32_16x16x32_bf16 v[58:61], v[164:167], v[216:219], 0
	v_mfma_f32_16x16x32_bf16 v[58:61], v[168:171], v[220:223], v[58:61]
	v_mfma_f32_16x16x32_bf16 v[50:53], v[176:179], v[220:223], 0
	v_mfma_f32_16x16x32_bf16 v[50:53], v[172:175], v[216:219], v[50:53]
	v_mfma_f32_16x16x32_bf16 v[34:37], v[172:175], v[192:195], 0
	v_mfma_f32_16x16x32_bf16 v[34:37], v[176:179], v[196:199], v[34:37]
	v_mfma_f32_16x16x32_bf16 v[42:45], v[168:171], v[196:199], 0
	v_mfma_f32_16x16x32_bf16 v[42:45], v[164:167], v[192:195], v[42:45]
	v_mfma_f32_16x16x32_bf16 v[26:29], v[164:167], v[200:203], 0
	v_mfma_f32_16x16x32_bf16 v[26:29], v[168:171], v[204:207], v[26:29]
	v_mfma_f32_16x16x32_bf16 v[18:21], v[176:179], v[204:207], 0
	v_mfma_f32_16x16x32_bf16 v[18:21], v[172:175], v[200:203], v[18:21]
	v_mfma_f32_16x16x32_bf16 v[2:5], v[172:175], v[208:211], 0
	v_mfma_f32_16x16x32_bf16 v[2:5], v[176:179], v[212:215], v[2:5]
	v_mfma_f32_16x16x32_bf16 v[10:13], v[168:171], v[212:215], 0
	v_mfma_f32_16x16x32_bf16 v[10:13], v[164:167], v[208:211], v[10:13]
	s_barrier
	s_setprio 0
	s_add_i32 s0, 0, 0x18000
	v_add_u32_e32 v145, s0, v143
	s_add_i32 s1, 0, 0x1c000
	ds_read_b128 v[148:151], v145
	ds_read_b128 v[152:155], v145 offset:1024
	ds_read_b128 v[156:159], v145 offset:2048
	ds_read_b128 v[160:163], v145 offset:3072
	v_add_u32_e32 v145, s1, v143
	ds_read_b128 v[164:167], v145
	ds_read_b128 v[168:171], v145 offset:1024
	ds_read_b128 v[172:175], v145 offset:2048
	ds_read_b128 v[176:179], v145 offset:3072
	s_add_u32 s26, s26, 0x80000
	s_addc_u32 s27, s27, 0
	s_mov_b32 m0, s37
	ds_read_b128 v[216:219], v144 offset:32768
	ds_read_b128 v[220:223], v144 offset:33792
	ds_read_b128 v[192:195], v144 offset:34816
	ds_read_b128 v[196:199], v144 offset:35840
	ds_read_b128 v[200:203], v144 offset:36864
	ds_read_b128 v[204:207], v144 offset:37888
	ds_read_b128 v[208:211], v144 offset:38912
	ds_read_b128 v[212:215], v144 offset:39936
	global_load_lds_dwordx4 v134, s[26:27]
	s_mov_b32 m0, s38
	s_nop 0
	global_load_lds_dwordx4 v132, s[26:27]
	s_waitcnt vmcnt(8)
	s_waitcnt lgkmcnt(0)
	s_setprio 1
	s_barrier

	v_mfma_f32_16x16x32_bf16 v[126:129], v[148:151], v[216:219], v[126:129]
	v_mfma_f32_16x16x32_bf16 v[126:129], v[152:155], v[220:223], v[126:129]
	v_mfma_f32_16x16x32_bf16 v[118:121], v[160:163], v[220:223], v[118:121]
	v_mfma_f32_16x16x32_bf16 v[118:121], v[156:159], v[216:219], v[118:121]
	v_mfma_f32_16x16x32_bf16 v[102:105], v[156:159], v[192:195], v[102:105]
	v_mfma_f32_16x16x32_bf16 v[102:105], v[160:163], v[196:199], v[102:105]
	v_mfma_f32_16x16x32_bf16 v[110:113], v[152:155], v[196:199], v[110:113]
	v_mfma_f32_16x16x32_bf16 v[110:113], v[148:151], v[192:195], v[110:113]
	v_mfma_f32_16x16x32_bf16 v[94:97], v[148:151], v[200:203], v[94:97]
	v_mfma_f32_16x16x32_bf16 v[94:97], v[152:155], v[204:207], v[94:97]
	v_mfma_f32_16x16x32_bf16 v[86:89], v[160:163], v[204:207], v[86:89]
	v_mfma_f32_16x16x32_bf16 v[86:89], v[156:159], v[200:203], v[86:89]
	v_mfma_f32_16x16x32_bf16 v[70:73], v[156:159], v[208:211], v[70:73]
	v_mfma_f32_16x16x32_bf16 v[70:73], v[160:163], v[212:215], v[70:73]
	v_mfma_f32_16x16x32_bf16 v[78:81], v[152:155], v[212:215], v[78:81]
	v_mfma_f32_16x16x32_bf16 v[78:81], v[148:151], v[208:211], v[78:81]


	v_mfma_f32_16x16x32_bf16 v[122:125], v[164:167], v[216:219], v[122:125]
	v_mfma_f32_16x16x32_bf16 v[122:125], v[168:171], v[220:223], v[122:125]
	v_mfma_f32_16x16x32_bf16 v[114:117], v[176:179], v[220:223], v[114:117]
	v_mfma_f32_16x16x32_bf16 v[114:117], v[172:175], v[216:219], v[114:117]
	v_mfma_f32_16x16x32_bf16 v[98:101], v[172:175], v[192:195], v[98:101]
	v_mfma_f32_16x16x32_bf16 v[98:101], v[176:179], v[196:199], v[98:101]
	v_mfma_f32_16x16x32_bf16 v[106:109], v[168:171], v[196:199], v[106:109]
	v_mfma_f32_16x16x32_bf16 v[106:109], v[164:167], v[192:195], v[106:109]
	v_mfma_f32_16x16x32_bf16 v[90:93], v[164:167], v[200:203], v[90:93]
	v_mfma_f32_16x16x32_bf16 v[90:93], v[168:171], v[204:207], v[90:93]
	v_mfma_f32_16x16x32_bf16 v[82:85], v[176:179], v[204:207], v[82:85]
	v_mfma_f32_16x16x32_bf16 v[82:85], v[172:175], v[200:203], v[82:85]
	v_mfma_f32_16x16x32_bf16 v[66:69], v[172:175], v[208:211], v[66:69]
	v_mfma_f32_16x16x32_bf16 v[66:69], v[176:179], v[212:215], v[66:69]
	v_mfma_f32_16x16x32_bf16 v[74:77], v[168:171], v[212:215], v[74:77]
	v_mfma_f32_16x16x32_bf16 v[74:77], v[164:167], v[208:211], v[74:77]
	s_barrier
	s_setprio 0
	s_add_i32 s0, s0, s31
	s_mov_b32 m0, s0
	ds_read_b128 v[216:219], v144 offset:49152
	ds_read_b128 v[220:223], v144 offset:50176
	ds_read_b128 v[192:195], v144 offset:51200
	ds_read_b128 v[196:199], v144 offset:52224
	ds_read_b128 v[200:203], v144 offset:53248
	ds_read_b128 v[204:207], v144 offset:54272
	ds_read_b128 v[208:211], v144 offset:55296
	ds_read_b128 v[212:215], v144 offset:56320
	s_add_u32 s100, s24, 0x80
	s_addc_u32 s101, s25, 0
	global_load_lds_dwordx4 v186, s[100:101]
	s_add_i32 m0, s0, 0x2000
	s_add_u32 s24, s24, 0x80080
	s_addc_u32 s25, s25, 0
	s_add_i32 s0, s1, s31
	s_add_u32 s100, s24, 0xfff80000
	s_addc_u32 s101, s25, -1
	global_load_lds_dwordx4 v130, s[100:101]
	s_mov_b32 m0, s0
	s_nop 0
	global_load_lds_dwordx4 v186, s[24:25]
	s_add_i32 m0, s0, 0x2000
	s_nop 0
	global_load_lds_dwordx4 v130, s[24:25]
	s_mov_b32 m0, s39
	s_nop 0
	s_add_u32 s100, s26, 0xfff80080
	s_addc_u32 s101, s27, -1
	global_load_lds_dwordx4 v134, s[100:101]
	s_mov_b32 m0, s40
	s_nop 0
	s_add_u32 s100, s26, 0xfff80080
	s_addc_u32 s101, s27, -1
	global_load_lds_dwordx4 v132, s[100:101]
	s_waitcnt vmcnt(8)
	s_waitcnt lgkmcnt(0)
	s_setprio 1
	s_barrier

	v_mfma_f32_16x16x32_bf16 v[62:65], v[148:151], v[216:219], v[62:65]
	v_mfma_f32_16x16x32_bf16 v[62:65], v[152:155], v[220:223], v[62:65]
	v_mfma_f32_16x16x32_bf16 v[54:57], v[160:163], v[220:223], v[54:57]
	v_mfma_f32_16x16x32_bf16 v[54:57], v[156:159], v[216:219], v[54:57]
	v_mfma_f32_16x16x32_bf16 v[38:41], v[156:159], v[192:195], v[38:41]
	v_mfma_f32_16x16x32_bf16 v[38:41], v[160:163], v[196:199], v[38:41]
	v_mfma_f32_16x16x32_bf16 v[46:49], v[152:155], v[196:199], v[46:49]
	v_mfma_f32_16x16x32_bf16 v[46:49], v[148:151], v[192:195], v[46:49]
	v_mfma_f32_16x16x32_bf16 v[30:33], v[148:151], v[200:203], v[30:33]
	v_mfma_f32_16x16x32_bf16 v[30:33], v[152:155], v[204:207], v[30:33]
	v_mfma_f32_16x16x32_bf16 v[22:25], v[160:163], v[204:207], v[22:25]
	v_mfma_f32_16x16x32_bf16 v[22:25], v[156:159], v[200:203], v[22:25]
	v_mfma_f32_16x16x32_bf16 v[6:9], v[156:159], v[208:211], v[6:9]
	v_mfma_f32_16x16x32_bf16 v[6:9], v[160:163], v[212:215], v[6:9]
	v_mfma_f32_16x16x32_bf16 v[14:17], v[152:155], v[212:215], v[14:17]
	v_mfma_f32_16x16x32_bf16 v[14:17], v[148:151], v[208:211], v[14:17]


	v_mfma_f32_16x16x32_bf16 v[58:61], v[164:167], v[216:219], v[58:61]
	v_mfma_f32_16x16x32_bf16 v[58:61], v[168:171], v[220:223], v[58:61]
	v_mfma_f32_16x16x32_bf16 v[50:53], v[176:179], v[220:223], v[50:53]
	v_mfma_f32_16x16x32_bf16 v[50:53], v[172:175], v[216:219], v[50:53]
	v_mfma_f32_16x16x32_bf16 v[34:37], v[172:175], v[192:195], v[34:37]
	v_mfma_f32_16x16x32_bf16 v[34:37], v[176:179], v[196:199], v[34:37]
	v_mfma_f32_16x16x32_bf16 v[42:45], v[168:171], v[196:199], v[42:45]
	v_mfma_f32_16x16x32_bf16 v[42:45], v[164:167], v[192:195], v[42:45]
	v_mfma_f32_16x16x32_bf16 v[26:29], v[164:167], v[200:203], v[26:29]
	v_mfma_f32_16x16x32_bf16 v[26:29], v[168:171], v[204:207], v[26:29]
	v_mfma_f32_16x16x32_bf16 v[18:21], v[176:179], v[204:207], v[18:21]
	v_mfma_f32_16x16x32_bf16 v[18:21], v[172:175], v[200:203], v[18:21]
	v_mfma_f32_16x16x32_bf16 v[2:5], v[172:175], v[208:211], v[2:5]
	v_mfma_f32_16x16x32_bf16 v[2:5], v[176:179], v[212:215], v[2:5]
	v_mfma_f32_16x16x32_bf16 v[10:13], v[168:171], v[212:215], v[10:13]
	v_mfma_f32_16x16x32_bf16 v[10:13], v[164:167], v[208:211], v[10:13]
	s_barrier
	s_setprio 0
	s_add_i32 s50, s50, 2
	s_add_u32 s22, s22, 0x100
	s_addc_u32 s23, s23, 0
	s_add_u32 s48, s48, 0x100
	s_addc_u32 s49, s49, 0
	s_cmp_gt_u32 s50, 29
	s_cbranch_scc0 .LBB0_159
.LBB0_159:
	s_add_u32 s0, s22, 0xfff80080
	s_addc_u32 s1, s23, -1
	s_add_i32 s51, 0, 0x10000
	s_cmp_eq_u32 s50, 28
	s_cselect_b32 s27, s15, s1
	s_cselect_b32 s26, s46, s0
	v_add_u32_e32 v140, s51, v143
	s_cselect_b32 s25, s13, s49
	s_cselect_b32 s24, s47, s48
	s_add_i32 s0, 0, 0x14000
	ds_read_b128 v[148:151], v140
	ds_read_b128 v[152:155], v140 offset:1024
	ds_read_b128 v[156:159], v140 offset:2048
	ds_read_b128 v[160:163], v140 offset:3072
	v_add_u32_e32 v140, s0, v143
	ds_read_b128 v[164:167], v140
	ds_read_b128 v[168:171], v140 offset:1024
	ds_read_b128 v[172:175], v140 offset:2048
	ds_read_b128 v[176:179], v140 offset:3072
	s_add_i32 m0, s35, 0xc000
	ds_read_b128 v[216:219], v144
	ds_read_b128 v[220:223], v144 offset:1024
	ds_read_b128 v[192:195], v144 offset:2048
	ds_read_b128 v[196:199], v144 offset:3072
	ds_read_b128 v[200:203], v144 offset:4096
	ds_read_b128 v[204:207], v144 offset:5120
	ds_read_b128 v[208:211], v144 offset:6144
	ds_read_b128 v[212:215], v144 offset:7168
	global_load_lds_dwordx4 v136, s[22:23]
	s_add_i32 m0, s35, 0xe000
	s_nop 0
	global_load_lds_dwordx4 v138, s[22:23]
	s_waitcnt vmcnt(8)
	s_waitcnt lgkmcnt(0)
	s_setprio 1
	s_barrier

	v_mfma_f32_16x16x32_bf16 v[126:129], v[148:151], v[216:219], v[126:129]
	v_mfma_f32_16x16x32_bf16 v[126:129], v[152:155], v[220:223], v[126:129]
	v_mfma_f32_16x16x32_bf16 v[118:121], v[160:163], v[220:223], v[118:121]
	v_mfma_f32_16x16x32_bf16 v[118:121], v[156:159], v[216:219], v[118:121]
	v_mfma_f32_16x16x32_bf16 v[102:105], v[156:159], v[192:195], v[102:105]
	v_mfma_f32_16x16x32_bf16 v[102:105], v[160:163], v[196:199], v[102:105]
	v_mfma_f32_16x16x32_bf16 v[110:113], v[152:155], v[196:199], v[110:113]
	v_mfma_f32_16x16x32_bf16 v[110:113], v[148:151], v[192:195], v[110:113]
	v_mfma_f32_16x16x32_bf16 v[94:97], v[148:151], v[200:203], v[94:97]
	v_mfma_f32_16x16x32_bf16 v[94:97], v[152:155], v[204:207], v[94:97]
	v_mfma_f32_16x16x32_bf16 v[86:89], v[160:163], v[204:207], v[86:89]
	v_mfma_f32_16x16x32_bf16 v[86:89], v[156:159], v[200:203], v[86:89]
	v_mfma_f32_16x16x32_bf16 v[70:73], v[156:159], v[208:211], v[70:73]
	v_mfma_f32_16x16x32_bf16 v[70:73], v[160:163], v[212:215], v[70:73]
	v_mfma_f32_16x16x32_bf16 v[78:81], v[152:155], v[212:215], v[78:81]
	v_mfma_f32_16x16x32_bf16 v[78:81], v[148:151], v[208:211], v[78:81]


	v_mfma_f32_16x16x32_bf16 v[122:125], v[164:167], v[216:219], v[122:125]
	v_mfma_f32_16x16x32_bf16 v[122:125], v[168:171], v[220:223], v[122:125]
	v_mfma_f32_16x16x32_bf16 v[114:117], v[176:179], v[220:223], v[114:117]
	v_mfma_f32_16x16x32_bf16 v[114:117], v[172:175], v[216:219], v[114:117]
	v_mfma_f32_16x16x32_bf16 v[98:101], v[172:175], v[192:195], v[98:101]
	v_mfma_f32_16x16x32_bf16 v[98:101], v[176:179], v[196:199], v[98:101]
	v_mfma_f32_16x16x32_bf16 v[106:109], v[168:171], v[196:199], v[106:109]
	v_mfma_f32_16x16x32_bf16 v[106:109], v[164:167], v[192:195], v[106:109]
	v_mfma_f32_16x16x32_bf16 v[90:93], v[164:167], v[200:203], v[90:93]
	v_mfma_f32_16x16x32_bf16 v[90:93], v[168:171], v[204:207], v[90:93]
	v_mfma_f32_16x16x32_bf16 v[82:85], v[176:179], v[204:207], v[82:85]
	v_mfma_f32_16x16x32_bf16 v[82:85], v[172:175], v[200:203], v[82:85]
	v_mfma_f32_16x16x32_bf16 v[66:69], v[172:175], v[208:211], v[66:69]
	v_mfma_f32_16x16x32_bf16 v[66:69], v[176:179], v[212:215], v[66:69]
	v_mfma_f32_16x16x32_bf16 v[74:77], v[168:171], v[212:215], v[74:77]
	v_mfma_f32_16x16x32_bf16 v[74:77], v[164:167], v[208:211], v[74:77]
	s_barrier
	s_setprio 0
	s_add_i32 s1, s51, s31
	s_mov_b32 m0, s1
	ds_read_b128 v[216:219], v144 offset:16384
	ds_read_b128 v[220:223], v144 offset:17408
	ds_read_b128 v[192:195], v144 offset:18432
	ds_read_b128 v[196:199], v144 offset:19456
	ds_read_b128 v[200:203], v144 offset:20480
	ds_read_b128 v[204:207], v144 offset:21504
	ds_read_b128 v[208:211], v144 offset:22528
	ds_read_b128 v[212:215], v144 offset:23552
	global_load_lds_dwordx4 v186, s[24:25]
	s_add_i32 m0, s1, 0x2000
	s_add_u32 s52, s24, 0x80000
	s_addc_u32 s53, s25, 0
	s_add_i32 s0, s0, s31
	global_load_lds_dwordx4 v130, s[24:25]
	s_mov_b32 m0, s0
	s_nop 0
	global_load_lds_dwordx4 v186, s[52:53]
	s_add_i32 m0, s0, 0x2000
	s_nop 0
	global_load_lds_dwordx4 v130, s[52:53]
	s_mov_b32 m0, s35
	s_nop 0
	global_load_lds_dwordx4 v134, s[26:27]
	s_mov_b32 m0, s36
	s_nop 0
	global_load_lds_dwordx4 v132, s[26:27]
	s_waitcnt vmcnt(8)
	s_waitcnt lgkmcnt(0)
	s_setprio 1
	s_barrier

	v_mfma_f32_16x16x32_bf16 v[62:65], v[148:151], v[216:219], v[62:65]
	v_mfma_f32_16x16x32_bf16 v[62:65], v[152:155], v[220:223], v[62:65]
	v_mfma_f32_16x16x32_bf16 v[54:57], v[160:163], v[220:223], v[54:57]
	v_mfma_f32_16x16x32_bf16 v[54:57], v[156:159], v[216:219], v[54:57]
	v_mfma_f32_16x16x32_bf16 v[38:41], v[156:159], v[192:195], v[38:41]
	v_mfma_f32_16x16x32_bf16 v[38:41], v[160:163], v[196:199], v[38:41]
	v_mfma_f32_16x16x32_bf16 v[46:49], v[152:155], v[196:199], v[46:49]
	v_mfma_f32_16x16x32_bf16 v[46:49], v[148:151], v[192:195], v[46:49]
	v_mfma_f32_16x16x32_bf16 v[30:33], v[148:151], v[200:203], v[30:33]
	v_mfma_f32_16x16x32_bf16 v[30:33], v[152:155], v[204:207], v[30:33]
	v_mfma_f32_16x16x32_bf16 v[22:25], v[160:163], v[204:207], v[22:25]
	v_mfma_f32_16x16x32_bf16 v[22:25], v[156:159], v[200:203], v[22:25]
	v_mfma_f32_16x16x32_bf16 v[6:9], v[156:159], v[208:211], v[6:9]
	v_mfma_f32_16x16x32_bf16 v[6:9], v[160:163], v[212:215], v[6:9]
	v_mfma_f32_16x16x32_bf16 v[14:17], v[152:155], v[212:215], v[14:17]
	v_mfma_f32_16x16x32_bf16 v[14:17], v[148:151], v[208:211], v[14:17]


	v_mfma_f32_16x16x32_bf16 v[58:61], v[164:167], v[216:219], v[58:61]
	v_mfma_f32_16x16x32_bf16 v[58:61], v[168:171], v[220:223], v[58:61]
	v_mfma_f32_16x16x32_bf16 v[50:53], v[176:179], v[220:223], v[50:53]
	v_mfma_f32_16x16x32_bf16 v[50:53], v[172:175], v[216:219], v[50:53]
	v_mfma_f32_16x16x32_bf16 v[34:37], v[172:175], v[192:195], v[34:37]
	v_mfma_f32_16x16x32_bf16 v[34:37], v[176:179], v[196:199], v[34:37]
	v_mfma_f32_16x16x32_bf16 v[42:45], v[168:171], v[196:199], v[42:45]
	v_mfma_f32_16x16x32_bf16 v[42:45], v[164:167], v[192:195], v[42:45]
	v_mfma_f32_16x16x32_bf16 v[26:29], v[164:167], v[200:203], v[26:29]
	v_mfma_f32_16x16x32_bf16 v[26:29], v[168:171], v[204:207], v[26:29]
	v_mfma_f32_16x16x32_bf16 v[18:21], v[176:179], v[204:207], v[18:21]
	v_mfma_f32_16x16x32_bf16 v[18:21], v[172:175], v[200:203], v[18:21]
	v_mfma_f32_16x16x32_bf16 v[2:5], v[172:175], v[208:211], v[2:5]
	v_mfma_f32_16x16x32_bf16 v[2:5], v[176:179], v[212:215], v[2:5]
	v_mfma_f32_16x16x32_bf16 v[10:13], v[168:171], v[212:215], v[10:13]
	v_mfma_f32_16x16x32_bf16 v[10:13], v[164:167], v[208:211], v[10:13]
	s_barrier
	s_setprio 0
	s_add_i32 s0, 0, 0x18000
	v_add_u32_e32 v145, s0, v143
	s_add_i32 s1, 0, 0x1c000
	ds_read_b128 v[148:151], v145
	ds_read_b128 v[152:155], v145 offset:1024
	ds_read_b128 v[156:159], v145 offset:2048
	ds_read_b128 v[160:163], v145 offset:3072
	v_add_u32_e32 v145, s1, v143
	ds_read_b128 v[164:167], v145
	ds_read_b128 v[168:171], v145 offset:1024
	ds_read_b128 v[172:175], v145 offset:2048
	ds_read_b128 v[176:179], v145 offset:3072
	s_add_u32 s26, s26, 0x80000
	s_addc_u32 s27, s27, 0
	s_mov_b32 m0, s37
	ds_read_b128 v[216:219], v144 offset:32768
	ds_read_b128 v[220:223], v144 offset:33792
	ds_read_b128 v[192:195], v144 offset:34816
	ds_read_b128 v[196:199], v144 offset:35840
	ds_read_b128 v[200:203], v144 offset:36864
	ds_read_b128 v[204:207], v144 offset:37888
	ds_read_b128 v[208:211], v144 offset:38912
	ds_read_b128 v[212:215], v144 offset:39936
	global_load_lds_dwordx4 v134, s[26:27]
	s_mov_b32 m0, s38
	s_nop 0
	global_load_lds_dwordx4 v132, s[26:27]
	s_waitcnt vmcnt(8)
	s_waitcnt lgkmcnt(0)
	s_setprio 1
	s_barrier

	v_mfma_f32_16x16x32_bf16 v[126:129], v[148:151], v[216:219], v[126:129]
	v_mfma_f32_16x16x32_bf16 v[126:129], v[152:155], v[220:223], v[126:129]
	v_mfma_f32_16x16x32_bf16 v[118:121], v[160:163], v[220:223], v[118:121]
	v_mfma_f32_16x16x32_bf16 v[118:121], v[156:159], v[216:219], v[118:121]
	v_mfma_f32_16x16x32_bf16 v[102:105], v[156:159], v[192:195], v[102:105]
	v_mfma_f32_16x16x32_bf16 v[102:105], v[160:163], v[196:199], v[102:105]
	v_mfma_f32_16x16x32_bf16 v[110:113], v[152:155], v[196:199], v[110:113]
	v_mfma_f32_16x16x32_bf16 v[110:113], v[148:151], v[192:195], v[110:113]
	v_mfma_f32_16x16x32_bf16 v[94:97], v[148:151], v[200:203], v[94:97]
	v_mfma_f32_16x16x32_bf16 v[94:97], v[152:155], v[204:207], v[94:97]
	v_mfma_f32_16x16x32_bf16 v[86:89], v[160:163], v[204:207], v[86:89]
	v_mfma_f32_16x16x32_bf16 v[86:89], v[156:159], v[200:203], v[86:89]
	v_mfma_f32_16x16x32_bf16 v[70:73], v[156:159], v[208:211], v[70:73]
	v_mfma_f32_16x16x32_bf16 v[70:73], v[160:163], v[212:215], v[70:73]
	v_mfma_f32_16x16x32_bf16 v[78:81], v[152:155], v[212:215], v[78:81]
	v_mfma_f32_16x16x32_bf16 v[78:81], v[148:151], v[208:211], v[78:81]


	v_mfma_f32_16x16x32_bf16 v[122:125], v[164:167], v[216:219], v[122:125]
	v_mfma_f32_16x16x32_bf16 v[122:125], v[168:171], v[220:223], v[122:125]
	v_mfma_f32_16x16x32_bf16 v[114:117], v[176:179], v[220:223], v[114:117]
	v_mfma_f32_16x16x32_bf16 v[114:117], v[172:175], v[216:219], v[114:117]
	v_mfma_f32_16x16x32_bf16 v[98:101], v[172:175], v[192:195], v[98:101]
	v_mfma_f32_16x16x32_bf16 v[98:101], v[176:179], v[196:199], v[98:101]
	v_mfma_f32_16x16x32_bf16 v[106:109], v[168:171], v[196:199], v[106:109]
	v_mfma_f32_16x16x32_bf16 v[106:109], v[164:167], v[192:195], v[106:109]
	v_mfma_f32_16x16x32_bf16 v[90:93], v[164:167], v[200:203], v[90:93]
	v_mfma_f32_16x16x32_bf16 v[90:93], v[168:171], v[204:207], v[90:93]
	v_mfma_f32_16x16x32_bf16 v[82:85], v[176:179], v[204:207], v[82:85]
	v_mfma_f32_16x16x32_bf16 v[82:85], v[172:175], v[200:203], v[82:85]
	v_mfma_f32_16x16x32_bf16 v[66:69], v[172:175], v[208:211], v[66:69]
	v_mfma_f32_16x16x32_bf16 v[66:69], v[176:179], v[212:215], v[66:69]
	v_mfma_f32_16x16x32_bf16 v[74:77], v[168:171], v[212:215], v[74:77]
	v_mfma_f32_16x16x32_bf16 v[74:77], v[164:167], v[208:211], v[74:77]
	s_barrier
	s_setprio 0
	s_add_i32 s0, s0, s31
	s_mov_b32 m0, s0
	ds_read_b128 v[216:219], v144 offset:49152
	ds_read_b128 v[220:223], v144 offset:50176
	ds_read_b128 v[192:195], v144 offset:51200
	ds_read_b128 v[196:199], v144 offset:52224
	ds_read_b128 v[200:203], v144 offset:53248
	ds_read_b128 v[204:207], v144 offset:54272
	ds_read_b128 v[208:211], v144 offset:55296
	ds_read_b128 v[212:215], v144 offset:56320
	s_add_u32 s100, s24, 0x80
	s_addc_u32 s101, s25, 0
	global_load_lds_dwordx4 v186, s[100:101]
	s_add_i32 m0, s0, 0x2000
	s_add_u32 s24, s24, 0x80080
	s_addc_u32 s25, s25, 0
	s_add_i32 s0, s1, s31
	s_add_u32 s100, s24, 0xfff80000
	s_addc_u32 s101, s25, -1
	global_load_lds_dwordx4 v130, s[100:101]
	s_mov_b32 m0, s0
	s_nop 0
	global_load_lds_dwordx4 v186, s[24:25]
	s_add_i32 m0, s0, 0x2000
	s_nop 0
	global_load_lds_dwordx4 v130, s[24:25]
	s_mov_b32 m0, s39
	s_nop 0
	s_add_u32 s100, s26, 0xfff80080
	s_addc_u32 s101, s27, -1
	global_load_lds_dwordx4 v134, s[100:101]
	s_mov_b32 m0, s40
	s_nop 0
	s_add_u32 s100, s26, 0xfff80080
	s_addc_u32 s101, s27, -1
	global_load_lds_dwordx4 v132, s[100:101]
	s_waitcnt vmcnt(8)
	s_waitcnt lgkmcnt(0)
	s_setprio 1
	s_barrier

	v_mfma_f32_16x16x32_bf16 v[62:65], v[148:151], v[216:219], v[62:65]
	v_mfma_f32_16x16x32_bf16 v[62:65], v[152:155], v[220:223], v[62:65]
	v_mfma_f32_16x16x32_bf16 v[54:57], v[160:163], v[220:223], v[54:57]
	v_mfma_f32_16x16x32_bf16 v[54:57], v[156:159], v[216:219], v[54:57]
	v_mfma_f32_16x16x32_bf16 v[38:41], v[156:159], v[192:195], v[38:41]
	v_mfma_f32_16x16x32_bf16 v[38:41], v[160:163], v[196:199], v[38:41]
	v_mfma_f32_16x16x32_bf16 v[46:49], v[152:155], v[196:199], v[46:49]
	v_mfma_f32_16x16x32_bf16 v[46:49], v[148:151], v[192:195], v[46:49]
	v_mfma_f32_16x16x32_bf16 v[30:33], v[148:151], v[200:203], v[30:33]
	v_mfma_f32_16x16x32_bf16 v[30:33], v[152:155], v[204:207], v[30:33]
	v_mfma_f32_16x16x32_bf16 v[22:25], v[160:163], v[204:207], v[22:25]
	v_mfma_f32_16x16x32_bf16 v[22:25], v[156:159], v[200:203], v[22:25]
	v_mfma_f32_16x16x32_bf16 v[6:9], v[156:159], v[208:211], v[6:9]
	v_mfma_f32_16x16x32_bf16 v[6:9], v[160:163], v[212:215], v[6:9]
	v_mfma_f32_16x16x32_bf16 v[14:17], v[152:155], v[212:215], v[14:17]
	v_mfma_f32_16x16x32_bf16 v[14:17], v[148:151], v[208:211], v[14:17]


	v_mfma_f32_16x16x32_bf16 v[58:61], v[164:167], v[216:219], v[58:61]
	v_mfma_f32_16x16x32_bf16 v[58:61], v[168:171], v[220:223], v[58:61]
	v_mfma_f32_16x16x32_bf16 v[50:53], v[176:179], v[220:223], v[50:53]
	v_mfma_f32_16x16x32_bf16 v[50:53], v[172:175], v[216:219], v[50:53]
	v_mfma_f32_16x16x32_bf16 v[34:37], v[172:175], v[192:195], v[34:37]
	v_mfma_f32_16x16x32_bf16 v[34:37], v[176:179], v[196:199], v[34:37]
	v_mfma_f32_16x16x32_bf16 v[42:45], v[168:171], v[196:199], v[42:45]
	v_mfma_f32_16x16x32_bf16 v[42:45], v[164:167], v[192:195], v[42:45]
	v_mfma_f32_16x16x32_bf16 v[26:29], v[164:167], v[200:203], v[26:29]
	v_mfma_f32_16x16x32_bf16 v[26:29], v[168:171], v[204:207], v[26:29]
	v_mfma_f32_16x16x32_bf16 v[18:21], v[176:179], v[204:207], v[18:21]
	v_mfma_f32_16x16x32_bf16 v[18:21], v[172:175], v[200:203], v[18:21]
	v_mfma_f32_16x16x32_bf16 v[2:5], v[172:175], v[208:211], v[2:5]
	v_mfma_f32_16x16x32_bf16 v[2:5], v[176:179], v[212:215], v[2:5]
	v_mfma_f32_16x16x32_bf16 v[10:13], v[168:171], v[212:215], v[10:13]
	v_mfma_f32_16x16x32_bf16 v[10:13], v[164:167], v[208:211], v[10:13]
	s_barrier
	s_setprio 0
	s_add_i32 s50, s50, 2
	s_add_u32 s22, s22, 0x100
	s_addc_u32 s23, s23, 0
	s_add_u32 s48, s48, 0x100
	s_addc_u32 s49, s49, 0
	s_cmp_gt_u32 s50, 29
	s_cbranch_scc0 .LBB0_159
	s_and_b64 vcc, exec, s[10:11]
	s_cbranch_vccz .LBB0_162
	s_barrier
